# clique barrier also at FFN2-down to next layer FFN1-up seam (layer 0); counters inside zeroed control area
# speedup vs baseline: 1.0298x; 1.0298x over previous
; __device__ __forceinline__ unsigned xb_ld(unsigned* p)              { return __hip_atomic_load(p, __ATOMIC_RELAXED, __HIP_MEMORY_SCOPE_AGENT); }
; __device__ __forceinline__ unsigned xb_add(unsigned* p, unsigned v) { return __hip_atomic_fetch_add(p, v, __ATOMIC_RELAXED, __HIP_MEMORY_SCOPE_AGENT); }
; #define XB_SPIN(cond, bar) do { unsigned _sp = 0; while (cond) { __builtin_amdgcn_s_sleep(1); \
;     if ((++_sp & 255u) == 0u) { if (xb_ld(&(bar)[XB_TMO])) break; if (_sp > XB_SPIN_CAP) { atomicAdd(&(bar)[XB_TMO], 1u); break; } } } } while (0)
; #define GSYNC() do { XcdBarrier xb_; xb_.bar = (unsigned*)(KARGS()->ws + WS_CTL) + 1024; xb_.x = xb_xcc_id(); xb_.st = (volatile LAS unsigned*)(lds + LDS_XB); xcd_barrier(xb_); } while (0)
; __device__ __forceinline__ void xcd_barrier(const XcdBarrier& b) {
;     asm volatile("s_waitcnt vmcnt(0)" ::: "memory");
;     __syncthreads();
;     if (threadIdx.x == 0) {
;         unsigned* bar = b.bar;
;         __builtin_amdgcn_s_waitcnt(0);
;         unsigned nloc = b.st[0], nx = b.st[1];
;         if (nloc == 0u) { xcd_barrier_complete(bar, b.x, nloc, nx); b.st[0] = nloc; b.st[1] = nx; }
;         const unsigned old = xb_add(&bar[XB_XSUB(b.x)], 1u);
;         const unsigned gen = old / nloc;
;         if (old + 1u == (gen + 1u) * nloc) {
;             __builtin_amdgcn_fence(__ATOMIC_RELEASE, "agent");
;             asm volatile("s_waitcnt vmcnt(0)" ::: "memory");
;             const unsigned og = xb_add(&bar[XB_TOP], 1u);
;             const unsigned tg = og / nx;
;             if (og + 1u == (tg + 1u) * nx) xb_add(&bar[XB_TOPGEN], 1u);
;             else XB_SPIN(xb_ld(&bar[XB_TOPGEN]) == tg, bar);
;             __builtin_amdgcn_fence(__ATOMIC_ACQUIRE, "agent");
;             xb_add(&bar[XB_XGEN(b.x)], 1u);
;             asm volatile("s_waitcnt vmcnt(0)" ::: "memory");
;         } else {
;             XB_SPIN(xb_ld(&bar[XB_XGEN(b.x)]) == gen, bar);
;             __builtin_amdgcn_fence(__ATOMIC_ACQUIRE, "agent");
;             asm volatile("s_waitcnt vmcnt(0)" ::: "memory");
;         }
;     }
;     __syncthreads();
; }
; __global__ void __launch_bounds__(512, 2) fwd_kernel(Args a) {
;     ...
;         GSYNC();
.LBB0_2105:
	s_mov_b64 s[8:9], s[0:1]
	s_getreg_b32 s2, hwreg(HW_REG_XCC_ID, 0, 4)
	s_waitcnt vmcnt(0)
	s_waitcnt lgkmcnt(0)
	v_readlane_b32 s6, v255, 0
	v_readlane_b32 s7, v255, 1
	s_barrier
	v_readlane_b32 s4, v255, 40
	v_readlane_b32 s5, v255, 10
	s_nop 1
	s_cmp_eq_u32 s4, 0
	s_cbranch_scc1 .Lfs6
	s_cmp_lg_u32 s5, 0
	s_cbranch_scc1 .Lfs6
	s_and_saveexec_b64 s[4:5], s[6:7]
	s_cbranch_execz .Lfe6
	s_load_dwordx2 s[8:9], s[0:1], 0x128
	v_readlane_b32 s10, v255, 41
	v_readlane_b32 s11, v255, 8
	s_nop 1
	s_and_b32 s11, s11, 63
	s_lshl_b32 s11, s11, 6
	s_addk_i32 s11, 0x6200
	v_mov_b32_e32 v2, 0
	v_mov_b32_e32 v3, 1
	s_add_i32 s10, s10, 1
	s_lshl_b32 s10, s10, 2
	s_waitcnt lgkmcnt(0)
	s_add_u32 s8, s8, s11
	s_addc_u32 s9, s9, 0
	global_atomic_add v2, v3, s[8:9]

; __device__ __forceinline__ unsigned xb_add(unsigned* p, unsigned v) { return __hip_atomic_fetch_add(p, v, __ATOMIC_RELAXED, __HIP_MEMORY_SCOPE_AGENT); }
; #define GSYNC() do { XcdBarrier xb_; xb_.bar = (unsigned*)(KARGS()->ws + WS_CTL) + 1024; xb_.x = xb_xcc_id(); xb_.st = (volatile LAS unsigned*)(lds + LDS_XB); xcd_barrier(xb_); } while (0)
; __device__ __forceinline__ void xcd_barrier(const XcdBarrier& b) {
;     asm volatile("s_waitcnt vmcnt(0)" ::: "memory");
;     __syncthreads();
;     if (threadIdx.x == 0) {
;         unsigned* bar = b.bar;
;         __builtin_amdgcn_s_waitcnt(0);
;         unsigned nloc = b.st[0], nx = b.st[1];
;         if (nloc == 0u) { xcd_barrier_complete(bar, b.x, nloc, nx); b.st[0] = nloc; b.st[1] = nx; }
;         const unsigned old = xb_add(&bar[XB_XSUB(b.x)], 1u);
; __global__ void __launch_bounds__(512, 2) fwd_kernel(Args a) {
;     ...
;         GSYNC();
.Lfs6:
	s_and_saveexec_b64 s[4:5], s[6:7]
	s_xor_b64 s[6:7], exec, s[4:5]
	s_cbranch_execnz .LBB0_2106
.Lfj6:
	s_getpc_b64 s[98:99]
